# up-GEMM epilogue: element-wise stages (affine start, -log2e scaling, 1+t, final multiplies) as packed f32 ops on dedicated register pairs; 20 fewer VALU instructions per 8-element row group
# speedup vs baseline: 1.0153x; 1.0032x over previous
.LBB0_1016:
	s_mov_b32 s100, 0xbfb8aa3b
	s_mov_b32 s101, 0xbfb8aa3b
	v_mov_b32_e32 v250, 1.0
	v_mov_b32_e32 v251, 1.0
	s_waitcnt vmcnt(0)
	v_pk_fma_f32 v[200:201], v[108:109], v[156:157], v[128:129]
	s_waitcnt lgkmcnt(4)
	s_nop 1
	v_fmac_f32_dpp v200, v108, v148 row_shr:1 row_mask:0xf bank_mask:0xf
	v_fmac_f32_dpp v200, v192, v148 row_shl:15 row_mask:0xf bank_mask:0xf
	v_fmac_f32_dpp v200, v108, v152 row_shl:1 row_mask:0xf bank_mask:0xf
	v_fmac_f32_dpp v200, v112, v152 row_shr:15 row_mask:0xf bank_mask:0xf
	v_fmac_f32_dpp v201, v109, v149 row_shr:1 row_mask:0xf bank_mask:0xf
	v_fmac_f32_dpp v201, v193, v149 row_shl:15 row_mask:0xf bank_mask:0xf
	v_fmac_f32_dpp v201, v109, v153 row_shl:1 row_mask:0xf bank_mask:0xf
	v_fmac_f32_dpp v201, v113, v153 row_shr:15 row_mask:0xf bank_mask:0xf
	v_pk_fma_f32 v[202:203], v[110:111], v[158:159], v[130:131]
	v_fmac_f32_dpp v202, v110, v150 row_shr:1 row_mask:0xf bank_mask:0xf
	v_fmac_f32_dpp v202, v194, v150 row_shl:15 row_mask:0xf bank_mask:0xf
	v_fmac_f32_dpp v202, v110, v154 row_shl:1 row_mask:0xf bank_mask:0xf
	v_fmac_f32_dpp v202, v114, v154 row_shr:15 row_mask:0xf bank_mask:0xf
	v_fmac_f32_dpp v203, v111, v151 row_shr:1 row_mask:0xf bank_mask:0xf
	v_fmac_f32_dpp v203, v195, v151 row_shl:15 row_mask:0xf bank_mask:0xf
	v_fmac_f32_dpp v203, v111, v155 row_shl:1 row_mask:0xf bank_mask:0xf
	v_fmac_f32_dpp v203, v115, v155 row_shr:15 row_mask:0xf bank_mask:0xf
	v_pk_fma_f32 v[204:205], v[104:105], v[144:145], v[120:121]
	s_waitcnt lgkmcnt(3)
	v_fmac_f32_dpp v204, v104, v136 row_shr:1 row_mask:0xf bank_mask:0xf
	v_fmac_f32_dpp v204, v188, v136 row_shl:15 row_mask:0xf bank_mask:0xf
	v_fmac_f32_dpp v204, v104, v140 row_shl:1 row_mask:0xf bank_mask:0xf
	v_fmac_f32_dpp v204, v100, v140 row_shr:15 row_mask:0xf bank_mask:0xf
	v_fmac_f32_dpp v205, v105, v137 row_shr:1 row_mask:0xf bank_mask:0xf
	v_fmac_f32_dpp v205, v189, v137 row_shl:15 row_mask:0xf bank_mask:0xf
	v_fmac_f32_dpp v205, v105, v141 row_shl:1 row_mask:0xf bank_mask:0xf
	v_fmac_f32_dpp v205, v101, v141 row_shr:15 row_mask:0xf bank_mask:0xf
	v_pk_fma_f32 v[206:207], v[106:107], v[146:147], v[122:123]
	v_fmac_f32_dpp v206, v106, v138 row_shr:1 row_mask:0xf bank_mask:0xf
	v_fmac_f32_dpp v206, v190, v138 row_shl:15 row_mask:0xf bank_mask:0xf
	v_fmac_f32_dpp v206, v106, v142 row_shl:1 row_mask:0xf bank_mask:0xf
	v_fmac_f32_dpp v206, v102, v142 row_shr:15 row_mask:0xf bank_mask:0xf
	v_fmac_f32_dpp v207, v107, v139 row_shr:1 row_mask:0xf bank_mask:0xf
	v_fmac_f32_dpp v207, v191, v139 row_shl:15 row_mask:0xf bank_mask:0xf
	v_fmac_f32_dpp v207, v107, v143 row_shl:1 row_mask:0xf bank_mask:0xf
	v_fmac_f32_dpp v207, v103, v143 row_shr:15 row_mask:0xf bank_mask:0xf
	v_pk_mul_f32 v[246:247], v[200:201], s[100:101]
	v_pk_mul_f32 v[248:249], v[202:203], s[100:101]
	v_pk_mul_f32 v[224:225], v[204:205], s[100:101]
	v_pk_mul_f32 v[228:229], v[206:207], s[100:101]
	v_exp_f32_e32 v246, v246
	v_exp_f32_e32 v247, v247
	v_exp_f32_e32 v248, v248
	v_exp_f32_e32 v249, v249
	v_exp_f32_e32 v224, v224
	v_exp_f32_e32 v225, v225
	v_exp_f32_e32 v228, v228
	v_exp_f32_e32 v229, v229
	v_pk_add_f32 v[246:247], v[246:247], v[250:251]
	v_pk_add_f32 v[248:249], v[248:249], v[250:251]
	v_pk_add_f32 v[224:225], v[224:225], v[250:251]
	v_pk_add_f32 v[228:229], v[228:229], v[250:251]
	v_rcp_f32_e32 v246, v246
	v_rcp_f32_e32 v247, v247
	v_rcp_f32_e32 v248, v248
	v_rcp_f32_e32 v249, v249
	v_rcp_f32_e32 v224, v224
	v_rcp_f32_e32 v225, v225
	v_rcp_f32_e32 v228, v228
	v_rcp_f32_e32 v229, v229
	s_nop 0
	v_pk_mul_f32 v[246:247], v[200:201], v[246:247]
	v_pk_mul_f32 v[248:249], v[202:203], v[248:249]
	v_pk_mul_f32 v[224:225], v[204:205], v[224:225]
	v_pk_mul_f32 v[228:229], v[206:207], v[228:229]
	v_pk_mul_f32 v[246:247], v[160:161], v[246:247]
	v_pk_mul_f32 v[248:249], v[162:163], v[248:249]
	v_pk_mul_f32 v[224:225], v[132:133], v[224:225]
	v_pk_mul_f32 v[228:229], v[134:135], v[228:229]
	v_lshl_add_u32 v240, s36, 8, v232
	v_cvt_pk_bf16_f32 v160, v246, v247
	v_cvt_pk_bf16_f32 v161, v248, v249
	v_cvt_pk_bf16_f32 v162, v224, v225
	v_mov_b64_e32 v[132:133], s[54:55]
	v_cvt_pk_bf16_f32 v163, v228, v229
	v_mad_i64_i32 v[188:189], s[4:5], v240, s79, v[132:133]
	v_lshlrev_b64 v[134:135], 1, v[222:223]
	v_lshl_add_u64 v[188:189], v[188:189], 0, v[134:135]
	global_store_dwordx4 v[188:189], v[160:163], off
	s_andn2_b64 vcc, exec, s[44:45]
	s_nop 0
	v_pk_fma_f32 v[200:201], v[112:113], v[156:157], v[128:129]
	v_fmac_f32_dpp v200, v112, v148 row_shr:1 row_mask:0xf bank_mask:0xf
	v_fmac_f32_dpp v200, v108, v148 row_shl:15 row_mask:0xf bank_mask:0xf
	v_fmac_f32_dpp v200, v112, v152 row_shl:1 row_mask:0xf bank_mask:0xf
	v_fmac_f32_dpp v200, v86, v152 row_shr:15 row_mask:0xf bank_mask:0xf
	v_fmac_f32_dpp v201, v113, v149 row_shr:1 row_mask:0xf bank_mask:0xf
	v_fmac_f32_dpp v201, v109, v149 row_shl:15 row_mask:0xf bank_mask:0xf
	v_fmac_f32_dpp v201, v113, v153 row_shl:1 row_mask:0xf bank_mask:0xf
	v_fmac_f32_dpp v201, v87, v153 row_shr:15 row_mask:0xf bank_mask:0xf
	v_pk_fma_f32 v[202:203], v[114:115], v[158:159], v[130:131]
	v_fmac_f32_dpp v202, v114, v150 row_shr:1 row_mask:0xf bank_mask:0xf
	v_fmac_f32_dpp v202, v110, v150 row_shl:15 row_mask:0xf bank_mask:0xf
	v_fmac_f32_dpp v202, v114, v154 row_shl:1 row_mask:0xf bank_mask:0xf
	v_fmac_f32_dpp v202, v88, v154 row_shr:15 row_mask:0xf bank_mask:0xf
	v_fmac_f32_dpp v203, v115, v151 row_shr:1 row_mask:0xf bank_mask:0xf
	v_fmac_f32_dpp v203, v111, v151 row_shl:15 row_mask:0xf bank_mask:0xf
	v_fmac_f32_dpp v203, v115, v155 row_shl:1 row_mask:0xf bank_mask:0xf
	v_fmac_f32_dpp v203, v89, v155 row_shr:15 row_mask:0xf bank_mask:0xf
	v_pk_fma_f32 v[204:205], v[100:101], v[144:145], v[120:121]
	v_fmac_f32_dpp v204, v100, v136 row_shr:1 row_mask:0xf bank_mask:0xf
	v_fmac_f32_dpp v204, v104, v136 row_shl:15 row_mask:0xf bank_mask:0xf
	v_fmac_f32_dpp v204, v100, v140 row_shl:1 row_mask:0xf bank_mask:0xf
	v_fmac_f32_dpp v204, v82, v140 row_shr:15 row_mask:0xf bank_mask:0xf
	v_fmac_f32_dpp v205, v101, v137 row_shr:1 row_mask:0xf bank_mask:0xf
	v_fmac_f32_dpp v205, v105, v137 row_shl:15 row_mask:0xf bank_mask:0xf
	v_fmac_f32_dpp v205, v101, v141 row_shl:1 row_mask:0xf bank_mask:0xf
	v_fmac_f32_dpp v205, v83, v141 row_shr:15 row_mask:0xf bank_mask:0xf
	v_pk_fma_f32 v[206:207], v[102:103], v[146:147], v[122:123]
	v_fmac_f32_dpp v206, v102, v138 row_shr:1 row_mask:0xf bank_mask:0xf
	v_fmac_f32_dpp v206, v106, v138 row_shl:15 row_mask:0xf bank_mask:0xf
	v_fmac_f32_dpp v206, v102, v142 row_shl:1 row_mask:0xf bank_mask:0xf
	v_fmac_f32_dpp v206, v84, v142 row_shr:15 row_mask:0xf bank_mask:0xf
	v_fmac_f32_dpp v207, v103, v139 row_shr:1 row_mask:0xf bank_mask:0xf
	v_fmac_f32_dpp v207, v107, v139 row_shl:15 row_mask:0xf bank_mask:0xf
	v_fmac_f32_dpp v207, v103, v143 row_shl:1 row_mask:0xf bank_mask:0xf
	v_fmac_f32_dpp v207, v85, v143 row_shr:15 row_mask:0xf bank_mask:0xf
	v_pk_mul_f32 v[246:247], v[200:201], s[100:101]
	v_pk_mul_f32 v[248:249], v[202:203], s[100:101]
	v_pk_mul_f32 v[224:225], v[204:205], s[100:101]
	v_pk_mul_f32 v[228:229], v[206:207], s[100:101]
	v_exp_f32_e32 v246, v246
	v_exp_f32_e32 v247, v247
	v_exp_f32_e32 v248, v248
	v_exp_f32_e32 v249, v249
	v_exp_f32_e32 v224, v224
	v_exp_f32_e32 v225, v225
	v_exp_f32_e32 v228, v228
	v_exp_f32_e32 v229, v229
	v_pk_add_f32 v[246:247], v[246:247], v[250:251]
	v_pk_add_f32 v[248:249], v[248:249], v[250:251]
	v_pk_add_f32 v[224:225], v[224:225], v[250:251]
	v_pk_add_f32 v[228:229], v[228:229], v[250:251]
	v_rcp_f32_e32 v246, v246
	v_rcp_f32_e32 v247, v247
	v_rcp_f32_e32 v248, v248
	v_rcp_f32_e32 v249, v249
	v_rcp_f32_e32 v224, v224
	v_rcp_f32_e32 v225, v225
	v_rcp_f32_e32 v228, v228
	v_rcp_f32_e32 v229, v229
	s_nop 0
	v_pk_mul_f32 v[246:247], v[200:201], v[246:247]
	v_pk_mul_f32 v[248:249], v[202:203], v[248:249]
	v_pk_mul_f32 v[224:225], v[204:205], v[224:225]
	v_pk_mul_f32 v[228:229], v[206:207], v[228:229]
	v_pk_mul_f32 v[246:247], v[124:125], v[246:247]
	v_pk_mul_f32 v[248:249], v[126:127], v[248:249]
	v_pk_mul_f32 v[224:225], v[116:117], v[224:225]
	v_pk_mul_f32 v[228:229], v[118:119], v[228:229]
	v_cvt_pk_bf16_f32 v104, v246, v247
	v_or_b32_e32 v108, 16, v240
	v_cvt_pk_bf16_f32 v105, v248, v249
	v_mad_i64_i32 v[108:109], s[4:5], v108, s79, v[132:133]
	v_lshl_add_u64 v[108:109], v[108:109], 0, v[134:135]
	v_cvt_pk_bf16_f32 v106, v224, v225
	v_cvt_pk_bf16_f32 v107, v228, v229
	global_store_dwordx4 v[108:109], v[104:107], off
	v_pk_fma_f32 v[204:205], v[82:83], v[144:145], v[120:121]
	v_fmac_f32_dpp v204, v82, v136 row_shr:1 row_mask:0xf bank_mask:0xf
	v_fmac_f32_dpp v204, v100, v136 row_shl:15 row_mask:0xf bank_mask:0xf
	v_fmac_f32_dpp v204, v82, v140 row_shl:1 row_mask:0xf bank_mask:0xf
	v_fmac_f32_dpp v204, v66, v140 row_shr:15 row_mask:0xf bank_mask:0xf
	v_fmac_f32_dpp v205, v83, v137 row_shr:1 row_mask:0xf bank_mask:0xf
	v_fmac_f32_dpp v205, v101, v137 row_shl:15 row_mask:0xf bank_mask:0xf
	v_fmac_f32_dpp v205, v83, v141 row_shl:1 row_mask:0xf bank_mask:0xf
	v_fmac_f32_dpp v205, v67, v141 row_shr:15 row_mask:0xf bank_mask:0xf
	v_pk_fma_f32 v[206:207], v[84:85], v[146:147], v[122:123]
	v_pk_fma_f32 v[200:201], v[86:87], v[156:157], v[128:129]
	v_fmac_f32_dpp v206, v84, v138 row_shr:1 row_mask:0xf bank_mask:0xf
	v_fmac_f32_dpp v206, v102, v138 row_shl:15 row_mask:0xf bank_mask:0xf
	v_fmac_f32_dpp v206, v84, v142 row_shl:1 row_mask:0xf bank_mask:0xf
	v_fmac_f32_dpp v206, v68, v142 row_shr:15 row_mask:0xf bank_mask:0xf
	v_fmac_f32_dpp v200, v86, v148 row_shr:1 row_mask:0xf bank_mask:0xf
	v_fmac_f32_dpp v200, v112, v148 row_shl:15 row_mask:0xf bank_mask:0xf
	v_fmac_f32_dpp v200, v86, v152 row_shl:1 row_mask:0xf bank_mask:0xf
	v_fmac_f32_dpp v200, v74, v152 row_shr:15 row_mask:0xf bank_mask:0xf
	v_fmac_f32_dpp v207, v85, v139 row_shr:1 row_mask:0xf bank_mask:0xf
	v_fmac_f32_dpp v207, v103, v139 row_shl:15 row_mask:0xf bank_mask:0xf
	v_fmac_f32_dpp v207, v85, v143 row_shl:1 row_mask:0xf bank_mask:0xf
	v_fmac_f32_dpp v207, v69, v143 row_shr:15 row_mask:0xf bank_mask:0xf
	v_fmac_f32_dpp v201, v87, v149 row_shr:1 row_mask:0xf bank_mask:0xf
	v_fmac_f32_dpp v201, v113, v149 row_shl:15 row_mask:0xf bank_mask:0xf
	v_fmac_f32_dpp v201, v87, v153 row_shl:1 row_mask:0xf bank_mask:0xf
	v_fmac_f32_dpp v201, v75, v153 row_shr:15 row_mask:0xf bank_mask:0xf
	v_pk_fma_f32 v[202:203], v[88:89], v[158:159], v[130:131]
	v_fmac_f32_dpp v202, v88, v150 row_shr:1 row_mask:0xf bank_mask:0xf
	v_fmac_f32_dpp v202, v114, v150 row_shl:15 row_mask:0xf bank_mask:0xf
	v_fmac_f32_dpp v202, v88, v154 row_shl:1 row_mask:0xf bank_mask:0xf
	v_fmac_f32_dpp v202, v76, v154 row_shr:15 row_mask:0xf bank_mask:0xf
	v_fmac_f32_dpp v203, v89, v151 row_shr:1 row_mask:0xf bank_mask:0xf
	v_fmac_f32_dpp v203, v115, v151 row_shl:15 row_mask:0xf bank_mask:0xf
	v_fmac_f32_dpp v203, v89, v155 row_shl:1 row_mask:0xf bank_mask:0xf
	v_fmac_f32_dpp v203, v77, v155 row_shr:15 row_mask:0xf bank_mask:0xf
	v_pk_mul_f32 v[246:247], v[200:201], s[100:101]
	v_pk_mul_f32 v[248:249], v[202:203], s[100:101]
	v_pk_mul_f32 v[224:225], v[204:205], s[100:101]
	v_pk_mul_f32 v[228:229], v[206:207], s[100:101]
	v_exp_f32_e32 v246, v246
	v_exp_f32_e32 v247, v247
	v_exp_f32_e32 v248, v248
	v_exp_f32_e32 v249, v249
	v_exp_f32_e32 v224, v224
	v_exp_f32_e32 v225, v225
	v_exp_f32_e32 v228, v228
	v_exp_f32_e32 v229, v229
	v_pk_add_f32 v[246:247], v[246:247], v[250:251]
	v_pk_add_f32 v[248:249], v[248:249], v[250:251]
	v_pk_add_f32 v[224:225], v[224:225], v[250:251]
	v_pk_add_f32 v[228:229], v[228:229], v[250:251]
	v_rcp_f32_e32 v246, v246
	v_rcp_f32_e32 v247, v247
	v_rcp_f32_e32 v248, v248
	v_rcp_f32_e32 v249, v249
	v_rcp_f32_e32 v224, v224
	v_rcp_f32_e32 v225, v225
	v_rcp_f32_e32 v228, v228
	v_rcp_f32_e32 v229, v229
	s_nop 0
	v_pk_mul_f32 v[246:247], v[200:201], v[246:247]
	v_pk_mul_f32 v[248:249], v[202:203], v[248:249]
	v_pk_mul_f32 v[224:225], v[204:205], v[224:225]
	v_pk_mul_f32 v[228:229], v[206:207], v[228:229]
	v_pk_mul_f32 v[246:247], v[94:95], v[246:247]
	v_pk_mul_f32 v[248:249], v[96:97], v[248:249]
	v_pk_mul_f32 v[224:225], v[90:91], v[224:225]
	v_pk_mul_f32 v[228:229], v[92:93], v[228:229]
	v_cvt_pk_bf16_f32 v90, v246, v247
	v_or_b32_e32 v94, 32, v240
	v_mad_i64_i32 v[94:95], s[4:5], v94, s79, v[132:133]
	v_lshl_add_u64 v[94:95], v[94:95], 0, v[134:135]
	v_cvt_pk_bf16_f32 v91, v248, v249
	v_cvt_pk_bf16_f32 v92, v224, v225
	v_cvt_pk_bf16_f32 v93, v228, v229
	global_store_dwordx4 v[94:95], v[90:93], off
	s_nop 1
	v_pk_fma_f32 v[200:201], v[74:75], v[156:157], v[128:129]
	s_nop 1
	v_fmac_f32_dpp v200, v74, v148 row_shr:1 row_mask:0xf bank_mask:0xf
	v_fmac_f32_dpp v200, v86, v148 row_shl:15 row_mask:0xf bank_mask:0xf
	v_fmac_f32_dpp v200, v74, v152 row_shl:1 row_mask:0xf bank_mask:0xf
	v_fmac_f32_dpp v200, v184, v152 row_shr:15 row_mask:0xf bank_mask:0xf
	v_fmac_f32_dpp v201, v75, v149 row_shr:1 row_mask:0xf bank_mask:0xf
	v_fmac_f32_dpp v201, v87, v149 row_shl:15 row_mask:0xf bank_mask:0xf
	v_fmac_f32_dpp v201, v75, v153 row_shl:1 row_mask:0xf bank_mask:0xf
	v_fmac_f32_dpp v201, v185, v153 row_shr:15 row_mask:0xf bank_mask:0xf
	v_pk_fma_f32 v[202:203], v[76:77], v[158:159], v[130:131]
	v_fmac_f32_dpp v202, v76, v150 row_shr:1 row_mask:0xf bank_mask:0xf
	v_fmac_f32_dpp v202, v88, v150 row_shl:15 row_mask:0xf bank_mask:0xf
	v_fmac_f32_dpp v202, v76, v154 row_shl:1 row_mask:0xf bank_mask:0xf
	v_fmac_f32_dpp v202, v186, v154 row_shr:15 row_mask:0xf bank_mask:0xf
	v_fmac_f32_dpp v203, v77, v151 row_shr:1 row_mask:0xf bank_mask:0xf
	v_fmac_f32_dpp v203, v89, v151 row_shl:15 row_mask:0xf bank_mask:0xf
	v_fmac_f32_dpp v203, v77, v155 row_shl:1 row_mask:0xf bank_mask:0xf
	v_fmac_f32_dpp v203, v187, v155 row_shr:15 row_mask:0xf bank_mask:0xf
	v_pk_fma_f32 v[204:205], v[66:67], v[144:145], v[120:121]
	s_waitcnt lgkmcnt(2)
	v_fmac_f32_dpp v204, v66, v136 row_shr:1 row_mask:0xf bank_mask:0xf
	v_fmac_f32_dpp v204, v82, v136 row_shl:15 row_mask:0xf bank_mask:0xf
	v_fmac_f32_dpp v204, v66, v140 row_shl:1 row_mask:0xf bank_mask:0xf
	v_fmac_f32_dpp v204, v180, v140 row_shr:15 row_mask:0xf bank_mask:0xf
	v_fmac_f32_dpp v205, v67, v137 row_shr:1 row_mask:0xf bank_mask:0xf
	v_fmac_f32_dpp v205, v83, v137 row_shl:15 row_mask:0xf bank_mask:0xf
	v_fmac_f32_dpp v205, v67, v141 row_shl:1 row_mask:0xf bank_mask:0xf
	v_fmac_f32_dpp v205, v181, v141 row_shr:15 row_mask:0xf bank_mask:0xf
	v_pk_fma_f32 v[206:207], v[68:69], v[146:147], v[122:123]
	v_fmac_f32_dpp v206, v68, v138 row_shr:1 row_mask:0xf bank_mask:0xf
	v_fmac_f32_dpp v206, v84, v138 row_shl:15 row_mask:0xf bank_mask:0xf
	v_fmac_f32_dpp v206, v68, v142 row_shl:1 row_mask:0xf bank_mask:0xf
	v_fmac_f32_dpp v206, v182, v142 row_shr:15 row_mask:0xf bank_mask:0xf
	v_fmac_f32_dpp v207, v69, v139 row_shr:1 row_mask:0xf bank_mask:0xf
	v_fmac_f32_dpp v207, v85, v139 row_shl:15 row_mask:0xf bank_mask:0xf
	v_fmac_f32_dpp v207, v69, v143 row_shl:1 row_mask:0xf bank_mask:0xf
	v_fmac_f32_dpp v207, v183, v143 row_shr:15 row_mask:0xf bank_mask:0xf
	v_pk_mul_f32 v[246:247], v[200:201], s[100:101]
	v_pk_mul_f32 v[248:249], v[202:203], s[100:101]
	v_pk_mul_f32 v[224:225], v[204:205], s[100:101]
	v_pk_mul_f32 v[228:229], v[206:207], s[100:101]
	v_exp_f32_e32 v246, v246
	v_exp_f32_e32 v247, v247
	v_exp_f32_e32 v248, v248
	v_exp_f32_e32 v249, v249
	v_exp_f32_e32 v224, v224
	v_exp_f32_e32 v225, v225
	v_exp_f32_e32 v228, v228
	v_exp_f32_e32 v229, v229
	v_pk_add_f32 v[246:247], v[246:247], v[250:251]
	v_pk_add_f32 v[248:249], v[248:249], v[250:251]
	v_pk_add_f32 v[224:225], v[224:225], v[250:251]
	v_pk_add_f32 v[228:229], v[228:229], v[250:251]
	v_rcp_f32_e32 v246, v246
	v_rcp_f32_e32 v247, v247
	v_rcp_f32_e32 v248, v248
	v_rcp_f32_e32 v249, v249
	v_rcp_f32_e32 v224, v224
	v_rcp_f32_e32 v225, v225
	v_rcp_f32_e32 v228, v228
	v_rcp_f32_e32 v229, v229
	s_nop 0
	v_pk_mul_f32 v[246:247], v[200:201], v[246:247]
	v_pk_mul_f32 v[248:249], v[202:203], v[248:249]
	v_pk_mul_f32 v[224:225], v[204:205], v[224:225]
	v_pk_mul_f32 v[228:229], v[206:207], v[228:229]
	v_pk_mul_f32 v[246:247], v[78:79], v[246:247]
	v_pk_mul_f32 v[248:249], v[80:81], v[248:249]
	v_pk_mul_f32 v[224:225], v[70:71], v[224:225]
	v_pk_mul_f32 v[228:229], v[72:73], v[228:229]
	v_cvt_pk_bf16_f32 v66, v246, v247
	v_cvt_pk_bf16_f32 v67, v248, v249
	v_cvt_pk_bf16_f32 v68, v224, v225
	v_or_b32_e32 v70, 48, v240
	v_mad_i64_i32 v[70:71], s[4:5], v70, s79, v[132:133]
	v_lshl_add_u64 v[70:71], v[70:71], 0, v[134:135]
	v_cvt_pk_bf16_f32 v69, v228, v229
	global_store_dwordx4 v[70:71], v[66:69], off
	v_pk_fma_f32 v[202:203], v[56:57], v[158:159], v[130:131]
	s_waitcnt lgkmcnt(1)
	v_fmac_f32_dpp v203, v57, v151 row_shr:1 row_mask:0xf bank_mask:0xf
	v_fmac_f32_dpp v203, v179, v151 row_shl:15 row_mask:0xf bank_mask:0xf
	v_fmac_f32_dpp v203, v57, v155 row_shl:1 row_mask:0xf bank_mask:0xf
	v_fmac_f32_dpp v203, v41, v155 row_shr:15 row_mask:0xf bank_mask:0xf
	v_pk_fma_f32 v[204:205], v[50:51], v[144:145], v[120:121]
	v_pk_fma_f32 v[200:201], v[54:55], v[156:157], v[128:129]
	s_nop 1
	v_fmac_f32_dpp v200, v54, v148 row_shr:1 row_mask:0xf bank_mask:0xf
	v_fmac_f32_dpp v200, v176, v148 row_shl:15 row_mask:0xf bank_mask:0xf
	v_fmac_f32_dpp v200, v54, v152 row_shl:1 row_mask:0xf bank_mask:0xf
	v_fmac_f32_dpp v200, v38, v152 row_shr:15 row_mask:0xf bank_mask:0xf
	v_fmac_f32_dpp v201, v55, v149 row_shr:1 row_mask:0xf bank_mask:0xf
	v_fmac_f32_dpp v201, v177, v149 row_shl:15 row_mask:0xf bank_mask:0xf
	v_fmac_f32_dpp v201, v55, v153 row_shl:1 row_mask:0xf bank_mask:0xf
	v_fmac_f32_dpp v201, v39, v153 row_shr:15 row_mask:0xf bank_mask:0xf
	v_fmac_f32_dpp v202, v56, v150 row_shr:1 row_mask:0xf bank_mask:0xf
	v_fmac_f32_dpp v202, v178, v150 row_shl:15 row_mask:0xf bank_mask:0xf
	v_fmac_f32_dpp v202, v56, v154 row_shl:1 row_mask:0xf bank_mask:0xf
	v_fmac_f32_dpp v202, v40, v154 row_shr:15 row_mask:0xf bank_mask:0xf
	s_waitcnt lgkmcnt(0)
	v_fmac_f32_dpp v204, v50, v136 row_shr:1 row_mask:0xf bank_mask:0xf
	v_fmac_f32_dpp v204, v172, v136 row_shl:15 row_mask:0xf bank_mask:0xf
	v_fmac_f32_dpp v204, v50, v140 row_shl:1 row_mask:0xf bank_mask:0xf
	v_fmac_f32_dpp v204, v34, v140 row_shr:15 row_mask:0xf bank_mask:0xf
	v_fmac_f32_dpp v205, v51, v137 row_shr:1 row_mask:0xf bank_mask:0xf
	v_fmac_f32_dpp v205, v173, v137 row_shl:15 row_mask:0xf bank_mask:0xf
	v_fmac_f32_dpp v205, v51, v141 row_shl:1 row_mask:0xf bank_mask:0xf
	v_fmac_f32_dpp v205, v35, v141 row_shr:15 row_mask:0xf bank_mask:0xf
	v_pk_fma_f32 v[206:207], v[52:53], v[146:147], v[122:123]
	v_fmac_f32_dpp v206, v52, v138 row_shr:1 row_mask:0xf bank_mask:0xf
	v_fmac_f32_dpp v206, v174, v138 row_shl:15 row_mask:0xf bank_mask:0xf
	v_fmac_f32_dpp v206, v52, v142 row_shl:1 row_mask:0xf bank_mask:0xf
	v_fmac_f32_dpp v206, v36, v142 row_shr:15 row_mask:0xf bank_mask:0xf
	v_fmac_f32_dpp v207, v53, v139 row_shr:1 row_mask:0xf bank_mask:0xf
	v_fmac_f32_dpp v207, v175, v139 row_shl:15 row_mask:0xf bank_mask:0xf
	v_fmac_f32_dpp v207, v53, v143 row_shl:1 row_mask:0xf bank_mask:0xf
	v_fmac_f32_dpp v207, v37, v143 row_shr:15 row_mask:0xf bank_mask:0xf
	v_pk_mul_f32 v[246:247], v[200:201], s[100:101]
	v_pk_mul_f32 v[248:249], v[202:203], s[100:101]
	v_pk_mul_f32 v[224:225], v[204:205], s[100:101]
	v_pk_mul_f32 v[228:229], v[206:207], s[100:101]
	v_exp_f32_e32 v246, v246
	v_exp_f32_e32 v247, v247
	v_exp_f32_e32 v248, v248
	v_exp_f32_e32 v249, v249
	v_exp_f32_e32 v224, v224
	v_exp_f32_e32 v225, v225
	v_exp_f32_e32 v228, v228
	v_exp_f32_e32 v229, v229
	v_pk_add_f32 v[246:247], v[246:247], v[250:251]
	v_pk_add_f32 v[248:249], v[248:249], v[250:251]
	v_pk_add_f32 v[224:225], v[224:225], v[250:251]
	v_pk_add_f32 v[228:229], v[228:229], v[250:251]
	v_rcp_f32_e32 v246, v246
	v_rcp_f32_e32 v247, v247
	v_rcp_f32_e32 v248, v248
	v_rcp_f32_e32 v249, v249
	v_rcp_f32_e32 v224, v224
	v_rcp_f32_e32 v225, v225
	v_rcp_f32_e32 v228, v228
	v_rcp_f32_e32 v229, v229
	s_nop 0
	v_pk_mul_f32 v[246:247], v[200:201], v[246:247]
	v_pk_mul_f32 v[248:249], v[202:203], v[248:249]
	v_pk_mul_f32 v[224:225], v[204:205], v[224:225]
	v_pk_mul_f32 v[228:229], v[206:207], v[228:229]
	v_pk_mul_f32 v[246:247], v[62:63], v[246:247]
	v_pk_mul_f32 v[248:249], v[64:65], v[248:249]
	v_pk_mul_f32 v[224:225], v[58:59], v[224:225]
	v_pk_mul_f32 v[228:229], v[60:61], v[228:229]
	v_add_u32_e32 v66, 0x80, v240
	v_cvt_pk_bf16_f32 v58, v246, v247
	v_mad_i64_i32 v[62:63], s[4:5], v66, s79, v[132:133]
	v_lshl_add_u64 v[62:63], v[62:63], 0, v[134:135]
	v_cvt_pk_bf16_f32 v59, v248, v249
	v_cvt_pk_bf16_f32 v60, v224, v225
	v_cvt_pk_bf16_f32 v61, v228, v229
	global_store_dwordx4 v[62:63], v[58:61], off
	s_nop 1
	v_pk_fma_f32 v[200:201], v[38:39], v[156:157], v[128:129]
	v_fmac_f32_dpp v200, v38, v148 row_shr:1 row_mask:0xf bank_mask:0xf
	v_fmac_f32_dpp v200, v54, v148 row_shl:15 row_mask:0xf bank_mask:0xf
	v_fmac_f32_dpp v200, v38, v152 row_shl:1 row_mask:0xf bank_mask:0xf
	v_fmac_f32_dpp v200, v22, v152 row_shr:15 row_mask:0xf bank_mask:0xf
	v_fmac_f32_dpp v201, v39, v149 row_shr:1 row_mask:0xf bank_mask:0xf
	v_fmac_f32_dpp v201, v55, v149 row_shl:15 row_mask:0xf bank_mask:0xf
	v_fmac_f32_dpp v201, v39, v153 row_shl:1 row_mask:0xf bank_mask:0xf
	v_fmac_f32_dpp v201, v23, v153 row_shr:15 row_mask:0xf bank_mask:0xf
	v_pk_fma_f32 v[202:203], v[40:41], v[158:159], v[130:131]
	v_fmac_f32_dpp v202, v40, v150 row_shr:1 row_mask:0xf bank_mask:0xf
	v_fmac_f32_dpp v202, v56, v150 row_shl:15 row_mask:0xf bank_mask:0xf
	v_fmac_f32_dpp v202, v40, v154 row_shl:1 row_mask:0xf bank_mask:0xf
	v_fmac_f32_dpp v202, v24, v154 row_shr:15 row_mask:0xf bank_mask:0xf
	v_fmac_f32_dpp v203, v41, v151 row_shr:1 row_mask:0xf bank_mask:0xf
	v_fmac_f32_dpp v203, v57, v151 row_shl:15 row_mask:0xf bank_mask:0xf
	v_fmac_f32_dpp v203, v41, v155 row_shl:1 row_mask:0xf bank_mask:0xf
	v_fmac_f32_dpp v203, v25, v155 row_shr:15 row_mask:0xf bank_mask:0xf
	v_pk_fma_f32 v[204:205], v[34:35], v[144:145], v[120:121]
	v_fmac_f32_dpp v204, v34, v136 row_shr:1 row_mask:0xf bank_mask:0xf
	v_fmac_f32_dpp v204, v50, v136 row_shl:15 row_mask:0xf bank_mask:0xf
	v_fmac_f32_dpp v204, v34, v140 row_shl:1 row_mask:0xf bank_mask:0xf
	v_fmac_f32_dpp v204, v18, v140 row_shr:15 row_mask:0xf bank_mask:0xf
	v_fmac_f32_dpp v205, v35, v137 row_shr:1 row_mask:0xf bank_mask:0xf
	v_fmac_f32_dpp v205, v51, v137 row_shl:15 row_mask:0xf bank_mask:0xf
	v_fmac_f32_dpp v205, v35, v141 row_shl:1 row_mask:0xf bank_mask:0xf
	v_fmac_f32_dpp v205, v19, v141 row_shr:15 row_mask:0xf bank_mask:0xf
	v_pk_fma_f32 v[206:207], v[36:37], v[146:147], v[122:123]
	v_fmac_f32_dpp v206, v36, v138 row_shr:1 row_mask:0xf bank_mask:0xf
	v_fmac_f32_dpp v206, v52, v138 row_shl:15 row_mask:0xf bank_mask:0xf
	v_fmac_f32_dpp v206, v36, v142 row_shl:1 row_mask:0xf bank_mask:0xf
	v_fmac_f32_dpp v206, v20, v142 row_shr:15 row_mask:0xf bank_mask:0xf
	v_fmac_f32_dpp v207, v37, v139 row_shr:1 row_mask:0xf bank_mask:0xf
	v_fmac_f32_dpp v207, v53, v139 row_shl:15 row_mask:0xf bank_mask:0xf
	v_fmac_f32_dpp v207, v37, v143 row_shl:1 row_mask:0xf bank_mask:0xf
	v_fmac_f32_dpp v207, v21, v143 row_shr:15 row_mask:0xf bank_mask:0xf
	v_pk_mul_f32 v[246:247], v[200:201], s[100:101]
	v_pk_mul_f32 v[248:249], v[202:203], s[100:101]
	v_pk_mul_f32 v[224:225], v[204:205], s[100:101]
	v_pk_mul_f32 v[228:229], v[206:207], s[100:101]
	v_exp_f32_e32 v246, v246
	v_exp_f32_e32 v247, v247
	v_exp_f32_e32 v248, v248
	v_exp_f32_e32 v249, v249
	v_exp_f32_e32 v224, v224
	v_exp_f32_e32 v225, v225
	v_exp_f32_e32 v228, v228
	v_exp_f32_e32 v229, v229
	v_pk_add_f32 v[246:247], v[246:247], v[250:251]
	v_pk_add_f32 v[248:249], v[248:249], v[250:251]
	v_pk_add_f32 v[224:225], v[224:225], v[250:251]
	v_pk_add_f32 v[228:229], v[228:229], v[250:251]
	v_rcp_f32_e32 v246, v246
	v_rcp_f32_e32 v247, v247
	v_rcp_f32_e32 v248, v248
	v_rcp_f32_e32 v249, v249
	v_rcp_f32_e32 v224, v224
	v_rcp_f32_e32 v225, v225
	v_rcp_f32_e32 v228, v228
	v_rcp_f32_e32 v229, v229
	s_nop 0
	v_pk_mul_f32 v[246:247], v[200:201], v[246:247]
	v_pk_mul_f32 v[248:249], v[202:203], v[248:249]
	v_pk_mul_f32 v[224:225], v[204:205], v[224:225]
	v_pk_mul_f32 v[228:229], v[206:207], v[228:229]
	v_pk_mul_f32 v[246:247], v[46:47], v[246:247]
	v_pk_mul_f32 v[248:249], v[48:49], v[248:249]
	v_pk_mul_f32 v[224:225], v[42:43], v[224:225]
	v_pk_mul_f32 v[228:229], v[44:45], v[228:229]
	v_cvt_pk_bf16_f32 v42, v246, v247
	v_add_u32_e32 v46, 0x90, v240
	v_mad_i64_i32 v[46:47], s[4:5], v46, s79, v[132:133]
	v_lshl_add_u64 v[46:47], v[46:47], 0, v[134:135]
	v_cvt_pk_bf16_f32 v43, v248, v249
	v_cvt_pk_bf16_f32 v44, v224, v225
	v_cvt_pk_bf16_f32 v45, v228, v229
	global_store_dwordx4 v[46:47], v[42:45], off
	s_nop 1
	v_pk_fma_f32 v[200:201], v[22:23], v[156:157], v[128:129]
	v_fmac_f32_dpp v200, v22, v148 row_shr:1 row_mask:0xf bank_mask:0xf
	v_fmac_f32_dpp v200, v38, v148 row_shl:15 row_mask:0xf bank_mask:0xf
	v_fmac_f32_dpp v200, v22, v152 row_shl:1 row_mask:0xf bank_mask:0xf
	v_fmac_f32_dpp v200, v14, v152 row_shr:15 row_mask:0xf bank_mask:0xf
	v_fmac_f32_dpp v201, v23, v149 row_shr:1 row_mask:0xf bank_mask:0xf
	v_fmac_f32_dpp v201, v39, v149 row_shl:15 row_mask:0xf bank_mask:0xf
	v_fmac_f32_dpp v201, v23, v153 row_shl:1 row_mask:0xf bank_mask:0xf
	v_fmac_f32_dpp v201, v15, v153 row_shr:15 row_mask:0xf bank_mask:0xf
	v_pk_fma_f32 v[202:203], v[24:25], v[158:159], v[130:131]
	v_fmac_f32_dpp v202, v24, v150 row_shr:1 row_mask:0xf bank_mask:0xf
	v_fmac_f32_dpp v202, v40, v150 row_shl:15 row_mask:0xf bank_mask:0xf
	v_fmac_f32_dpp v202, v24, v154 row_shl:1 row_mask:0xf bank_mask:0xf
	v_fmac_f32_dpp v202, v16, v154 row_shr:15 row_mask:0xf bank_mask:0xf
	v_fmac_f32_dpp v203, v25, v151 row_shr:1 row_mask:0xf bank_mask:0xf
	v_fmac_f32_dpp v203, v41, v151 row_shl:15 row_mask:0xf bank_mask:0xf
	v_fmac_f32_dpp v203, v25, v155 row_shl:1 row_mask:0xf bank_mask:0xf
	v_fmac_f32_dpp v203, v17, v155 row_shr:15 row_mask:0xf bank_mask:0xf
	v_pk_fma_f32 v[204:205], v[18:19], v[144:145], v[120:121]
	v_fmac_f32_dpp v204, v18, v136 row_shr:1 row_mask:0xf bank_mask:0xf
	v_fmac_f32_dpp v204, v34, v136 row_shl:15 row_mask:0xf bank_mask:0xf
	v_fmac_f32_dpp v204, v18, v140 row_shl:1 row_mask:0xf bank_mask:0xf
	v_fmac_f32_dpp v204, v10, v140 row_shr:15 row_mask:0xf bank_mask:0xf
	v_fmac_f32_dpp v205, v19, v137 row_shr:1 row_mask:0xf bank_mask:0xf
	v_fmac_f32_dpp v205, v35, v137 row_shl:15 row_mask:0xf bank_mask:0xf
	v_fmac_f32_dpp v205, v19, v141 row_shl:1 row_mask:0xf bank_mask:0xf
	v_fmac_f32_dpp v205, v11, v141 row_shr:15 row_mask:0xf bank_mask:0xf
	v_pk_fma_f32 v[206:207], v[20:21], v[146:147], v[122:123]
	v_fmac_f32_dpp v206, v20, v138 row_shr:1 row_mask:0xf bank_mask:0xf
	v_fmac_f32_dpp v206, v36, v138 row_shl:15 row_mask:0xf bank_mask:0xf
	v_fmac_f32_dpp v206, v20, v142 row_shl:1 row_mask:0xf bank_mask:0xf
	v_fmac_f32_dpp v206, v12, v142 row_shr:15 row_mask:0xf bank_mask:0xf
	v_fmac_f32_dpp v207, v21, v139 row_shr:1 row_mask:0xf bank_mask:0xf
	v_fmac_f32_dpp v207, v37, v139 row_shl:15 row_mask:0xf bank_mask:0xf
	v_fmac_f32_dpp v207, v21, v143 row_shl:1 row_mask:0xf bank_mask:0xf
	v_fmac_f32_dpp v207, v13, v143 row_shr:15 row_mask:0xf bank_mask:0xf
	v_pk_mul_f32 v[246:247], v[200:201], s[100:101]
	v_pk_mul_f32 v[248:249], v[202:203], s[100:101]
	v_pk_mul_f32 v[224:225], v[204:205], s[100:101]
	v_pk_mul_f32 v[228:229], v[206:207], s[100:101]
	v_exp_f32_e32 v246, v246
	v_exp_f32_e32 v247, v247
	v_exp_f32_e32 v248, v248
	v_exp_f32_e32 v249, v249
	v_exp_f32_e32 v224, v224
	v_exp_f32_e32 v225, v225
	v_exp_f32_e32 v228, v228
	v_exp_f32_e32 v229, v229
	v_pk_add_f32 v[246:247], v[246:247], v[250:251]
	v_pk_add_f32 v[248:249], v[248:249], v[250:251]
	v_pk_add_f32 v[224:225], v[224:225], v[250:251]
	v_pk_add_f32 v[228:229], v[228:229], v[250:251]
	v_rcp_f32_e32 v246, v246
	v_rcp_f32_e32 v247, v247
	v_rcp_f32_e32 v248, v248
	v_rcp_f32_e32 v249, v249
	v_rcp_f32_e32 v224, v224
	v_rcp_f32_e32 v225, v225
	v_rcp_f32_e32 v228, v228
	v_rcp_f32_e32 v229, v229
	s_nop 0
	v_pk_mul_f32 v[246:247], v[200:201], v[246:247]
	v_pk_mul_f32 v[248:249], v[202:203], v[248:249]
	v_pk_mul_f32 v[224:225], v[204:205], v[224:225]
	v_pk_mul_f32 v[228:229], v[206:207], v[228:229]
	v_pk_mul_f32 v[246:247], v[30:31], v[246:247]
	v_pk_mul_f32 v[248:249], v[32:33], v[248:249]
	v_pk_mul_f32 v[224:225], v[26:27], v[224:225]
	v_pk_mul_f32 v[228:229], v[28:29], v[228:229]
	v_cvt_pk_bf16_f32 v26, v246, v247
	v_add_u32_e32 v30, 0xa0, v240
	v_mad_i64_i32 v[30:31], s[4:5], v30, s79, v[132:133]
	v_lshl_add_u64 v[30:31], v[30:31], 0, v[134:135]
	v_cvt_pk_bf16_f32 v27, v248, v249
	v_cvt_pk_bf16_f32 v28, v224, v225
	v_cvt_pk_bf16_f32 v29, v228, v229
	global_store_dwordx4 v[30:31], v[26:29], off
	v_pk_fma_f32 v[206:207], v[12:13], v[146:147], v[122:123]
	v_pk_fma_f32 v[202:203], v[16:17], v[158:159], v[130:131]
	v_pk_fma_f32 v[200:201], v[14:15], v[156:157], v[128:129]
	s_nop 1
	v_fmac_f32_dpp v200, v14, v148 row_shr:1 row_mask:0xf bank_mask:0xf
	v_fmac_f32_dpp v200, v22, v148 row_shl:15 row_mask:0xf bank_mask:0xf
	v_fmac_f32_dpp v200, v14, v152 row_shl:1 row_mask:0xf bank_mask:0xf
	v_fmac_f32_dpp v200, v168, v152 row_shr:15 row_mask:0xf bank_mask:0xf
	v_fmac_f32_dpp v201, v15, v149 row_shr:1 row_mask:0xf bank_mask:0xf
	v_fmac_f32_dpp v201, v23, v149 row_shl:15 row_mask:0xf bank_mask:0xf
	v_fmac_f32_dpp v201, v15, v153 row_shl:1 row_mask:0xf bank_mask:0xf
	v_fmac_f32_dpp v201, v169, v153 row_shr:15 row_mask:0xf bank_mask:0xf
	v_fmac_f32_dpp v202, v16, v150 row_shr:1 row_mask:0xf bank_mask:0xf
	v_fmac_f32_dpp v202, v24, v150 row_shl:15 row_mask:0xf bank_mask:0xf
	v_fmac_f32_dpp v202, v16, v154 row_shl:1 row_mask:0xf bank_mask:0xf
	v_fmac_f32_dpp v202, v170, v154 row_shr:15 row_mask:0xf bank_mask:0xf
	v_pk_fma_f32 v[204:205], v[10:11], v[144:145], v[120:121]
	v_fmac_f32_dpp v204, v10, v136 row_shr:1 row_mask:0xf bank_mask:0xf
	v_fmac_f32_dpp v204, v18, v136 row_shl:15 row_mask:0xf bank_mask:0xf
	v_fmac_f32_dpp v204, v10, v140 row_shl:1 row_mask:0xf bank_mask:0xf
	v_fmac_f32_dpp v204, v164, v140 row_shr:15 row_mask:0xf bank_mask:0xf
	v_fmac_f32_dpp v205, v11, v137 row_shr:1 row_mask:0xf bank_mask:0xf
	v_fmac_f32_dpp v205, v19, v137 row_shl:15 row_mask:0xf bank_mask:0xf
	v_fmac_f32_dpp v205, v11, v141 row_shl:1 row_mask:0xf bank_mask:0xf
	v_fmac_f32_dpp v205, v165, v141 row_shr:15 row_mask:0xf bank_mask:0xf
	v_fmac_f32_dpp v206, v12, v138 row_shr:1 row_mask:0xf bank_mask:0xf
	v_fmac_f32_dpp v206, v20, v138 row_shl:15 row_mask:0xf bank_mask:0xf
	v_fmac_f32_dpp v206, v12, v142 row_shl:1 row_mask:0xf bank_mask:0xf
	v_fmac_f32_dpp v206, v166, v142 row_shr:15 row_mask:0xf bank_mask:0xf
	v_fmac_f32_dpp v207, v13, v139 row_shr:1 row_mask:0xf bank_mask:0xf
	v_fmac_f32_dpp v207, v21, v139 row_shl:15 row_mask:0xf bank_mask:0xf
	v_fmac_f32_dpp v207, v13, v143 row_shl:1 row_mask:0xf bank_mask:0xf
	v_fmac_f32_dpp v207, v167, v143 row_shr:15 row_mask:0xf bank_mask:0xf
	v_fmac_f32_dpp v203, v17, v151 row_shr:1 row_mask:0xf bank_mask:0xf
	v_fmac_f32_dpp v203, v25, v151 row_shl:15 row_mask:0xf bank_mask:0xf
	v_fmac_f32_dpp v203, v17, v155 row_shl:1 row_mask:0xf bank_mask:0xf
	v_fmac_f32_dpp v203, v171, v155 row_shr:15 row_mask:0xf bank_mask:0xf
	v_pk_mul_f32 v[246:247], v[200:201], s[100:101]
	v_pk_mul_f32 v[248:249], v[202:203], s[100:101]
	v_pk_mul_f32 v[224:225], v[204:205], s[100:101]
	v_pk_mul_f32 v[228:229], v[206:207], s[100:101]
	v_exp_f32_e32 v246, v246
	v_exp_f32_e32 v247, v247
	v_exp_f32_e32 v248, v248
	v_exp_f32_e32 v249, v249
	v_exp_f32_e32 v224, v224
	v_exp_f32_e32 v225, v225
	v_exp_f32_e32 v228, v228
	v_exp_f32_e32 v229, v229
	v_pk_add_f32 v[246:247], v[246:247], v[250:251]
	v_pk_add_f32 v[248:249], v[248:249], v[250:251]
	v_pk_add_f32 v[224:225], v[224:225], v[250:251]
	v_pk_add_f32 v[228:229], v[228:229], v[250:251]
	v_rcp_f32_e32 v246, v246
	v_rcp_f32_e32 v247, v247
	v_rcp_f32_e32 v248, v248
	v_rcp_f32_e32 v249, v249
	v_rcp_f32_e32 v224, v224
	v_rcp_f32_e32 v225, v225
	v_rcp_f32_e32 v228, v228
	v_rcp_f32_e32 v229, v229
	s_nop 0
	v_pk_mul_f32 v[246:247], v[200:201], v[246:247]
	v_pk_mul_f32 v[248:249], v[202:203], v[248:249]
	v_pk_mul_f32 v[224:225], v[204:205], v[224:225]
	v_pk_mul_f32 v[228:229], v[206:207], v[228:229]
	v_pk_mul_f32 v[246:247], v[6:7], v[246:247]
	v_pk_mul_f32 v[248:249], v[8:9], v[248:249]
	v_pk_mul_f32 v[224:225], v[2:3], v[224:225]
	v_pk_mul_f32 v[228:229], v[4:5], v[228:229]
	v_cvt_pk_bf16_f32 v2, v246, v247
	v_add_u32_e32 v6, 0xb0, v240
	v_mad_i64_i32 v[6:7], s[4:5], v6, s79, v[132:133]
	v_lshl_add_u64 v[6:7], v[6:7], 0, v[134:135]
	s_mov_b64 s[4:5], -1
	v_cvt_pk_bf16_f32 v3, v248, v249
	v_cvt_pk_bf16_f32 v4, v224, v225
	v_cvt_pk_bf16_f32 v5, v228, v229
	global_store_dwordx4 v[6:7], v[2:5], off
	s_cbranch_vccnz .LBB0_972
	s_and_b64 vcc, exec, s[46:47]
	s_cbranch_vccnz .LBB0_971
	s_barrier
	s_branch .LBB0_971

.LBB0_1074:
	v_mov_b64_e32 v[200:201], 0x100
	v_mov_b64_e32 v[202:203], 0xff
	v_mov_b64_e32 v[204:205], 0x80
	v_mov_b64_e32 v[206:207], 0x7f
	v_mov_b32_e32 v224, 0x358637bd
	v_mov_b32_e32 v225, 0x260
	v_mov_b32_e32 v228, 0xf149f2ca
	v_mov_b32_e32 v229, 0x220000
	v_mov_b64_e32 v[250:251], 0x550
	s_cmp_le_i32 s50, s6
	s_cselect_b64 s[4:5], -1, 0
	s_cmp_lt_i32 s6, s51
	s_cselect_b64 s[6:7], -1, 0
	s_and_b64 s[6:7], s[4:5], s[6:7]
	s_mov_b64 s[4:5], -1
	s_and_b64 vcc, exec, s[6:7]
	s_cbranch_vccnz .LBB0_1076
	s_add_i32 s6, s17, 11
	s_mov_b64 s[4:5], 0
